# back-edge rotation (guide 7.11): K-loop counter/offset/compare SALU moved from behind the loop-back barrier into the s_nop hazard slots of the last DMA group (in-proj, V^T, GLU loops)
# baseline (speedup 1.0000x reference)
; #define PG8_STAGE(bufoff, goff, voff) do { _Pragma("unroll") for (int _i = 0; _i < 2; ++_i) \
;         __builtin_amdgcn_raw_ptr_buffer_load_lds(R_##voff, (LAS void*)(lds + (bufoff) + ldsw + _i * 8192), 16, (int)(voff)[_i], (int)(goff), 0, 0); } while (0)
; #define PG8_WAIT_V(n) asm volatile("s_waitcnt vmcnt(" #n ")" ::: "memory")
; #define PG8_WAIT_L(n) asm volatile("s_waitcnt lgkmcnt(" #n ")" ::: "memory")
; #define PG8_BAR __builtin_amdgcn_s_barrier()
; #define PG8_SCHED __builtin_amdgcn_sched_barrier(0)
; template <class Epi, class Sched, bool ALIGN_EPI, bool SP2>
; __device__ __forceinline__ void gemm_phase(LAS unsigned char* lds, const Gemm g, const Sched& S, const Epi& E, int tid_in) {
;     ...
;             PG8_LDB(B0, 0, 0); PG8_LDB(B1, 0, 1); PG8_SCHED; PG8_LDA(At, 0, 0); PG8_STAGE(PG8_SA(1, 1), a1 + hstepA, voffA);
;             PG8_WAIT_V(8); PG8_WAIT_L(0); PG8_BAR; PG8_MMA(0, 0, At, B0); PG8_MMA(0, 1, At, B1); PG8_BAR; PG8_SCHED;
;             PG8_LDA(At, 0, 1); PG8_STAGE(PG8_SB(0, 0), b2, voffB); PG8_STAGE(PG8_SB(0, 1), b2 + hstepB, voffB); PG8_STAGE(PG8_SA(0, 0), a2, voffA);
;             PG8_WAIT_V(8); PG8_WAIT_L(0); PG8_BAR; PG8_MMA(1, 0, At, B0); PG8_MMA(1, 1, At, B1); PG8_BAR; PG8_SCHED;
.LBB0_98:
	v_add_u32_e32 v70, 0x10000, v241
	v_add_u32_e32 v152, 0x14000, v241
	ds_read_b128 v[50:53], v70
	ds_read_b128 v[54:57], v70 offset:1024
	ds_read_b128 v[66:69], v70 offset:2048
	ds_read_b128 v[70:73], v70 offset:3072
	ds_read_b128 v[132:135], v152
	ds_read_b128 v[136:139], v152 offset:1024
	ds_read_b128 v[148:151], v152 offset:2048
	ds_read_b128 v[152:155], v152 offset:3072
	s_add_i32 s14, s16, 0xfffc0080
	s_cmp_eq_u32 s19, 12
	s_cselect_b32 s27, s2, s14
	s_cselect_b32 s25, s3, s17
	s_or_b32 s20, s27, 0x80
	s_mov_b32 m0, s71
	ds_read_b128 v[156:159], v242
	ds_read_b128 v[160:163], v242 offset:1024
	ds_read_b128 v[164:167], v242 offset:2048
	ds_read_b128 v[168:171], v242 offset:3072
	ds_read_b128 v[180:183], v242 offset:4096
	ds_read_b128 v[184:187], v242 offset:5120
	ds_read_b128 v[188:191], v242 offset:6144
	ds_read_b128 v[192:195], v242 offset:7168
	buffer_load_dwordx4 v0, s[84:87], s16 offen lds
	s_mov_b32 m0, s73
	s_nop 0
	buffer_load_dwordx4 v237, s[84:87], s16 offen lds
	s_waitcnt vmcnt(8)
	s_waitcnt lgkmcnt(0)
	s_barrier
	s_setprio 1
	s_waitcnt lgkmcnt(6)
	v_mfma_f32_16x16x128_f8f6f4 v[176:179], v[50:57], v[156:163], v[176:179]
	v_mfma_f32_16x16x128_f8f6f4 v[172:175], v[66:73], v[156:163], v[172:175]
	s_waitcnt lgkmcnt(4)
	v_mfma_f32_16x16x128_f8f6f4 v[128:131], v[50:57], v[164:171], v[128:131]
	v_mfma_f32_16x16x128_f8f6f4 v[124:127], v[66:73], v[164:171], v[124:127]
	s_waitcnt lgkmcnt(2)
	v_mfma_f32_16x16x128_f8f6f4 v[196:199], v[50:57], v[180:187], v[110:113]
	v_mfma_f32_16x16x128_f8f6f4 v[200:203], v[66:73], v[180:187], v[106:109]
	s_waitcnt lgkmcnt(0)
	v_mfma_f32_16x16x128_f8f6f4 v[204:207], v[50:57], v[188:195], v[94:97]
	v_mfma_f32_16x16x128_f8f6f4 v[208:211], v[66:73], v[188:195], v[90:93]
	v_mfma_f32_16x16x128_f8f6f4 v[144:147], v[132:139], v[156:163], v[144:147]
	v_mfma_f32_16x16x128_f8f6f4 v[140:143], v[148:155], v[156:163], v[140:143]
	v_mfma_f32_16x16x128_f8f6f4 v[120:123], v[132:139], v[164:171], v[120:123]
	v_mfma_f32_16x16x128_f8f6f4 v[116:119], v[148:155], v[164:171], v[116:119]
	v_mfma_f32_16x16x128_f8f6f4 v[156:159], v[132:139], v[180:187], v[102:105]
	v_mfma_f32_16x16x128_f8f6f4 v[160:163], v[148:155], v[180:187], v[98:101]
	v_mfma_f32_16x16x128_f8f6f4 v[164:167], v[132:139], v[188:195], v[86:89]
	v_mfma_f32_16x16x128_f8f6f4 v[168:171], v[148:155], v[188:195], v[82:85]
	s_setprio 0
	s_barrier
	s_mov_b32 m0, s12
	s_mov_b32 s42, s86
	s_mov_b32 s43, s87
	s_nop 1
	ds_read_b128 v[82:85], v242 offset:16384
	ds_read_b128 v[86:89], v242 offset:17408
	ds_read_b128 v[90:93], v242 offset:18432
	ds_read_b128 v[94:97], v242 offset:19456
	ds_read_b128 v[98:101], v242 offset:20480
	ds_read_b128 v[102:105], v242 offset:21504
	ds_read_b128 v[106:109], v242 offset:22528
	ds_read_b128 v[110:113], v242 offset:23552
	buffer_load_dwordx4 v115, s[40:43], s25 offen lds
	s_mov_b32 m0, s13
	s_add_i32 s14, s25, 0x10000
	buffer_load_dwordx4 v238, s[40:43], s25 offen lds
	s_mov_b32 m0, s53
	s_nop 0
	buffer_load_dwordx4 v115, s[40:43], s14 offen lds
	s_mov_b32 m0, s58
	s_nop 0
	buffer_load_dwordx4 v238, s[40:43], s14 offen lds
	s_mov_b32 m0, s9
	s_nop 0
	buffer_load_dwordx4 v0, s[84:87], s27 offen lds
	s_mov_b32 m0, s59
	s_nop 0
	buffer_load_dwordx4 v237, s[84:87], s27 offen lds
	s_waitcnt vmcnt(8)
	s_waitcnt lgkmcnt(0)
	s_barrier
	s_setprio 1
	s_waitcnt lgkmcnt(6)
	v_mfma_f32_16x16x128_f8f6f4 v[78:81], v[50:57], v[82:89], v[78:81]
	v_mfma_f32_16x16x128_f8f6f4 v[74:77], v[66:73], v[82:89], v[74:77]
	s_waitcnt lgkmcnt(4)
	v_mfma_f32_16x16x128_f8f6f4 v[180:183], v[50:57], v[90:97], v[46:49]
	v_mfma_f32_16x16x128_f8f6f4 v[184:187], v[66:73], v[90:97], v[42:45]
	s_waitcnt lgkmcnt(2)
	v_mfma_f32_16x16x128_f8f6f4 v[188:191], v[50:57], v[98:105], v[30:33]
	v_mfma_f32_16x16x128_f8f6f4 v[192:195], v[66:73], v[98:105], v[26:29]
	s_waitcnt lgkmcnt(0)
	v_mfma_f32_16x16x128_f8f6f4 v[212:215], v[50:57], v[106:113], v[14:17]
	v_mfma_f32_16x16x128_f8f6f4 v[216:219], v[66:73], v[106:113], v[10:13]
	v_mfma_f32_16x16x128_f8f6f4 v[62:65], v[132:139], v[82:89], v[62:65]
	v_mfma_f32_16x16x128_f8f6f4 v[58:61], v[148:155], v[82:89], v[58:61]
	v_mfma_f32_16x16x128_f8f6f4 v[220:223], v[132:139], v[90:97], v[38:41]
	v_mfma_f32_16x16x128_f8f6f4 v[224:227], v[148:155], v[90:97], v[34:37]
	v_mfma_f32_16x16x128_f8f6f4 v[228:231], v[132:139], v[98:105], v[22:25]
	v_mfma_f32_16x16x128_f8f6f4 v[244:247], v[148:155], v[98:105], v[18:21]
	v_mfma_f32_16x16x128_f8f6f4 v[248:251], v[132:139], v[106:113], v[6:9]
	v_mfma_f32_16x16x128_f8f6f4 v[232:235], v[148:155], v[106:113], v[2:5]
	s_setprio 0
	s_barrier
; #define PG8_STAGE(bufoff, goff, voff) do { _Pragma("unroll") for (int _i = 0; _i < 2; ++_i) \
;         __builtin_amdgcn_raw_ptr_buffer_load_lds(R_##voff, (LAS void*)(lds + (bufoff) + ldsw + _i * 8192), 16, (int)(voff)[_i], (int)(goff), 0, 0); } while (0)
; #define PG8_WAIT_V(n) asm volatile("s_waitcnt vmcnt(" #n ")" ::: "memory")
; #define PG8_WAIT_L(n) asm volatile("s_waitcnt lgkmcnt(" #n ")" ::: "memory")
; #define PG8_BAR __builtin_amdgcn_s_barrier()
; #define PG8_SCHED __builtin_amdgcn_sched_barrier(0)
; template <class Epi, class Sched, bool ALIGN_EPI, bool SP2>
; __device__ __forceinline__ void gemm_phase(LAS unsigned char* lds, const Gemm g, const Sched& S, const Epi& E, int tid_in) {
;     ...
;         for (int t = 0; t < nt; t += 2) {
;             const bool last = (t == nt - 2);
;             const unsigned a1 = cA + (unsigned)(t + 1) * kstep;
;             const unsigned a2 = last ? nA : cA + (unsigned)(t + 2) * kstep, b2 = last ? nB : cB + (unsigned)(t + 2) * kstep;
;             const unsigned a3 = a2 + kstep, b3 = b2 + kstep;
;             if constexpr (Epi::MIDK) { if (t == g.kmid) E.midk(acc, wr, fr); }
;             if constexpr (SP2) {
;             PG8_LDB(B0, 0, 0); PG8_LDB(B1, 0, 1); PG8_SCHED; PG8_LDA(At, 0, 0); PG8_STAGE(PG8_SA(1, 1), a1 + hstepA, voffA);
;             PG8_WAIT_V(8); PG8_WAIT_L(0); PG8_BAR; PG8_MMA(0, 0, At, B0); PG8_MMA(0, 1, At, B1); PG8_BAR; PG8_SCHED;
;             PG8_LDA(At, 0, 1); PG8_STAGE(PG8_SB(0, 0), b2, voffB); PG8_STAGE(PG8_SB(0, 1), b2 + hstepB, voffB); PG8_STAGE(PG8_SA(0, 0), a2, voffA);
;             PG8_WAIT_V(8); PG8_WAIT_L(0); PG8_BAR; PG8_MMA(1, 0, At, B0); PG8_MMA(1, 1, At, B1); PG8_BAR; PG8_SCHED;
;             PG8_LDB(B0, 1, 0); PG8_LDB(B1, 1, 1); PG8_SCHED; PG8_LDA(At, 1, 0); PG8_STAGE(PG8_SA(0, 1), a2 + hstepA, voffA);
;             PG8_WAIT_V(8); PG8_WAIT_L(0); PG8_BAR; PG8_MMA(0, 0, At, B0); PG8_MMA(0, 1, At, B1); PG8_BAR; PG8_SCHED;
;             PG8_LDA(At, 1, 1); PG8_STAGE(PG8_SB(1, 0), b3, voffB); PG8_STAGE(PG8_SB(1, 1), b3 + hstepB, voffB); PG8_STAGE(PG8_SA(1, 0), a3, voffA);
;             PG8_WAIT_V(8); PG8_WAIT_L(0); PG8_BAR; PG8_MMA(1, 0, At, B0); PG8_MMA(1, 1, At, B1); PG8_BAR; PG8_SCHED;
	v_add_u32_e32 v10, 0x18000, v241
	s_nop 3
	ds_read_b128 v[2:5], v10
	ds_read_b128 v[6:9], v10 offset:1024
	ds_read_b128 v[18:21], v10 offset:2048
	ds_read_b128 v[22:25], v10 offset:3072
	v_add_u32_e32 v10, 0x1c000, v241
	ds_read_b128 v[50:53], v10
	ds_read_b128 v[54:57], v10 offset:1024
	ds_read_b128 v[66:69], v10 offset:2048
	ds_read_b128 v[70:73], v10 offset:3072
	s_add_i32 s27, s27, 0x40000
	s_mov_b32 m0, s60
	ds_read_b128 v[10:13], v242 offset:32768
	ds_read_b128 v[14:17], v242 offset:33792
	ds_read_b128 v[26:29], v242 offset:34816
	ds_read_b128 v[30:33], v242 offset:35840
	ds_read_b128 v[34:37], v242 offset:36864
	ds_read_b128 v[38:41], v242 offset:37888
	ds_read_b128 v[42:45], v242 offset:38912
	ds_read_b128 v[46:49], v242 offset:39936
	buffer_load_dwordx4 v0, s[84:87], s27 offen lds
	s_mov_b32 m0, s61
	s_nop 0
	buffer_load_dwordx4 v237, s[84:87], s27 offen lds
	s_waitcnt vmcnt(8)
	s_waitcnt lgkmcnt(0)
	s_barrier
	s_setprio 1
	s_waitcnt lgkmcnt(6)
	v_mfma_f32_16x16x128_f8f6f4 v[176:179], v[2:9], v[10:17], v[176:179]
	v_mfma_f32_16x16x128_f8f6f4 v[172:175], v[18:25], v[10:17], v[172:175]
	s_waitcnt lgkmcnt(4)
	v_mfma_f32_16x16x128_f8f6f4 v[128:131], v[2:9], v[26:33], v[128:131]
	v_mfma_f32_16x16x128_f8f6f4 v[124:127], v[18:25], v[26:33], v[124:127]
	s_waitcnt lgkmcnt(2)
	v_mfma_f32_16x16x128_f8f6f4 v[110:113], v[2:9], v[34:41], v[196:199]
	v_mfma_f32_16x16x128_f8f6f4 v[106:109], v[18:25], v[34:41], v[200:203]
	s_waitcnt lgkmcnt(0)
	v_mfma_f32_16x16x128_f8f6f4 v[94:97], v[2:9], v[42:49], v[204:207]
	v_mfma_f32_16x16x128_f8f6f4 v[90:93], v[18:25], v[42:49], v[208:211]
	v_mfma_f32_16x16x128_f8f6f4 v[144:147], v[50:57], v[10:17], v[144:147]
	v_mfma_f32_16x16x128_f8f6f4 v[140:143], v[66:73], v[10:17], v[140:143]
	v_mfma_f32_16x16x128_f8f6f4 v[120:123], v[50:57], v[26:33], v[120:123]
	v_mfma_f32_16x16x128_f8f6f4 v[116:119], v[66:73], v[26:33], v[116:119]
	v_mfma_f32_16x16x128_f8f6f4 v[102:105], v[50:57], v[34:41], v[156:159]
	v_mfma_f32_16x16x128_f8f6f4 v[98:101], v[66:73], v[34:41], v[160:163]
	v_mfma_f32_16x16x128_f8f6f4 v[86:89], v[50:57], v[42:49], v[164:167]
	v_mfma_f32_16x16x128_f8f6f4 v[82:85], v[66:73], v[42:49], v[168:171]
	s_setprio 0
	s_barrier
	s_mov_b32 m0, s49
	s_or_b32 s14, s25, 0x80
	ds_read_b128 v[34:37], v242 offset:49152
	ds_read_b128 v[38:41], v242 offset:50176
	ds_read_b128 v[132:135], v242 offset:51200
	ds_read_b128 v[136:139], v242 offset:52224
	ds_read_b128 v[148:151], v242 offset:53248
	ds_read_b128 v[152:155], v242 offset:54272
	ds_read_b128 v[156:159], v242 offset:55296
	ds_read_b128 v[160:163], v242 offset:56320
	buffer_load_dwordx4 v115, s[40:43], s14 offen lds
	s_mov_b32 m0, s31
	s_add_i32 s25, s25, 0x10080
	buffer_load_dwordx4 v238, s[40:43], s14 offen lds
	s_mov_b32 m0, s67
	s_add_i32 s19, s19, 2
	buffer_load_dwordx4 v115, s[40:43], s25 offen lds
	s_mov_b32 m0, s68
	s_addk_i32 s16, 0x100
	buffer_load_dwordx4 v238, s[40:43], s25 offen lds
	s_mov_b32 m0, s30
	s_addk_i32 s17, 0x100
	buffer_load_dwordx4 v0, s[84:87], s20 offen lds
	s_mov_b32 m0, s66
	s_cmp_gt_u32 s19, 13
	buffer_load_dwordx4 v237, s[84:87], s20 offen lds
	s_waitcnt vmcnt(8)
	s_waitcnt lgkmcnt(0)
	s_barrier
	s_setprio 1
	s_waitcnt lgkmcnt(6)
	v_mfma_f32_16x16x128_f8f6f4 v[78:81], v[2:9], v[34:41], v[78:81]
	v_mfma_f32_16x16x128_f8f6f4 v[74:77], v[18:25], v[34:41], v[74:77]
	s_waitcnt lgkmcnt(4)
	v_mfma_f32_16x16x128_f8f6f4 v[46:49], v[2:9], v[132:139], v[180:183]
	v_mfma_f32_16x16x128_f8f6f4 v[42:45], v[18:25], v[132:139], v[184:187]
	s_waitcnt lgkmcnt(2)
	v_mfma_f32_16x16x128_f8f6f4 v[30:33], v[2:9], v[148:155], v[188:191]
	v_mfma_f32_16x16x128_f8f6f4 v[26:29], v[18:25], v[148:155], v[192:195]
	s_waitcnt lgkmcnt(0)
	v_mfma_f32_16x16x128_f8f6f4 v[14:17], v[2:9], v[156:163], v[212:215]
	v_mfma_f32_16x16x128_f8f6f4 v[10:13], v[18:25], v[156:163], v[216:219]
	v_mfma_f32_16x16x128_f8f6f4 v[62:65], v[50:57], v[34:41], v[62:65]
	v_mfma_f32_16x16x128_f8f6f4 v[58:61], v[66:73], v[34:41], v[58:61]
	v_mfma_f32_16x16x128_f8f6f4 v[38:41], v[50:57], v[132:139], v[220:223]
	v_mfma_f32_16x16x128_f8f6f4 v[34:37], v[66:73], v[132:139], v[224:227]
	v_mfma_f32_16x16x128_f8f6f4 v[22:25], v[50:57], v[148:155], v[228:231]
	v_mfma_f32_16x16x128_f8f6f4 v[18:21], v[66:73], v[148:155], v[244:247]
	v_mfma_f32_16x16x128_f8f6f4 v[6:9], v[50:57], v[156:163], v[248:251]
	v_mfma_f32_16x16x128_f8f6f4 v[2:5], v[66:73], v[156:163], v[232:235]
	s_setprio 0
	s_barrier
	s_cbranch_scc0 .LBB0_98
	s_and_b64 vcc, exec, s[56:57]
	s_cbranch_vccz .LBB0_101
	s_barrier

; #define PG8_STAGE(bufoff, goff, voff) do { _Pragma("unroll") for (int _i = 0; _i < 2; ++_i) \
;         __builtin_amdgcn_raw_ptr_buffer_load_lds(R_##voff, (LAS void*)(lds + (bufoff) + ldsw + _i * 8192), 16, (int)(voff)[_i], (int)(goff), 0, 0); } while (0)
; #define PG8_WAIT_V(n) asm volatile("s_waitcnt vmcnt(" #n ")" ::: "memory")
; #define PG8_WAIT_L(n) asm volatile("s_waitcnt lgkmcnt(" #n ")" ::: "memory")
; #define PG8_BAR __builtin_amdgcn_s_barrier()
; #define PG8_SCHED __builtin_amdgcn_sched_barrier(0)
; template <class Epi, class Sched, bool ALIGN_EPI, bool SP2>
; __device__ __forceinline__ void gemm_phase(LAS unsigned char* lds, const Gemm g, const Sched& S, const Epi& E, int tid_in) {
;     ...
;             PG8_LDB(B0, 0, 0); PG8_LDB(B1, 0, 1); PG8_SCHED; PG8_LDA(At, 0, 0); PG8_STAGE(PG8_SA(1, 1), a1 + hstepA, voffA);
;             PG8_WAIT_V(8); PG8_WAIT_L(0); PG8_BAR; PG8_MMA(0, 0, At, B0); PG8_MMA(0, 1, At, B1); PG8_BAR; PG8_SCHED;
;             PG8_LDA(At, 0, 1); PG8_STAGE(PG8_SB(0, 0), b2, voffB); PG8_STAGE(PG8_SB(0, 1), b2 + hstepB, voffB); PG8_STAGE(PG8_SA(0, 0), a2, voffA);
;             PG8_WAIT_V(8); PG8_WAIT_L(0); PG8_BAR; PG8_MMA(1, 0, At, B0); PG8_MMA(1, 1, At, B1); PG8_BAR; PG8_SCHED;
.LBB0_137:
	v_add_u32_e32 v0, 0x10000, v193
	ds_read_b128 v[2:5], v0
	ds_read_b128 v[6:9], v0 offset:1024
	ds_read_b128 v[10:13], v0 offset:2048
	ds_read_b128 v[14:17], v0 offset:3072
	v_add_u32_e32 v0, 0x14000, v193
	ds_read_b128 v[18:21], v0
	ds_read_b128 v[22:25], v0 offset:1024
	ds_read_b128 v[26:29], v0 offset:2048
	ds_read_b128 v[30:33], v0 offset:3072
	s_add_i32 s11, s4, 0xfff00080
	s_cmp_eq_u32 s10, 60
	s_cselect_b32 s13, s3, s11
	s_cselect_b32 s12, s2, s5
	s_or_b32 s11, s13, 0x80
	s_mov_b32 m0, s8
	ds_read_b128 v[164:167], v194
	ds_read_b128 v[168:171], v194 offset:1024
	ds_read_b128 v[172:175], v194 offset:2048
	ds_read_b128 v[176:179], v194 offset:3072
	ds_read_b128 v[180:183], v194 offset:4096
	ds_read_b128 v[184:187], v194 offset:5120
	ds_read_b128 v[196:199], v194 offset:6144
	ds_read_b128 v[200:203], v194 offset:7168
	buffer_load_dwordx4 v115, s[40:43], s4 offen lds
	s_mov_b32 m0, s16
	s_nop 0
	buffer_load_dwordx4 v189, s[40:43], s4 offen lds
	s_waitcnt vmcnt(8)
	s_waitcnt lgkmcnt(0)
	s_barrier
	s_waitcnt lgkmcnt(7)
	v_mfma_f32_16x16x32_bf16 v[46:49], v[2:5], v[164:167], v[46:49]
	v_mfma_f32_16x16x32_bf16 v[42:45], v[10:13], v[164:167], v[42:45]
	s_waitcnt lgkmcnt(5)
	v_mfma_f32_16x16x32_bf16 v[160:163], v[2:5], v[172:175], v[160:163]
	v_mfma_f32_16x16x32_bf16 v[156:159], v[10:13], v[172:175], v[156:159]
	s_waitcnt lgkmcnt(3)
	v_mfma_f32_16x16x32_bf16 v[144:147], v[2:5], v[180:183], v[144:147]
	v_mfma_f32_16x16x32_bf16 v[140:143], v[10:13], v[180:183], v[140:143]
	s_waitcnt lgkmcnt(1)
	v_mfma_f32_16x16x32_bf16 v[62:65], v[2:5], v[196:199], v[62:65]
	v_mfma_f32_16x16x32_bf16 v[58:61], v[10:13], v[196:199], v[58:61]
	v_mfma_f32_16x16x32_bf16 v[46:49], v[6:9], v[168:171], v[46:49]
	v_mfma_f32_16x16x32_bf16 v[42:45], v[14:17], v[168:171], v[42:45]
	v_mfma_f32_16x16x32_bf16 v[160:163], v[6:9], v[176:179], v[160:163]
	v_mfma_f32_16x16x32_bf16 v[156:159], v[14:17], v[176:179], v[156:159]
	v_mfma_f32_16x16x32_bf16 v[144:147], v[6:9], v[184:187], v[144:147]
	v_mfma_f32_16x16x32_bf16 v[140:143], v[14:17], v[184:187], v[140:143]
	s_waitcnt lgkmcnt(0)
	v_mfma_f32_16x16x32_bf16 v[62:65], v[6:9], v[200:203], v[62:65]
	v_mfma_f32_16x16x32_bf16 v[58:61], v[14:17], v[200:203], v[58:61]
	v_mfma_f32_16x16x32_bf16 v[38:41], v[18:21], v[164:167], v[38:41]
	v_mfma_f32_16x16x32_bf16 v[34:37], v[26:29], v[164:167], v[34:37]
	v_mfma_f32_16x16x32_bf16 v[152:155], v[18:21], v[172:175], v[152:155]
	v_mfma_f32_16x16x32_bf16 v[148:151], v[26:29], v[172:175], v[148:151]
	v_mfma_f32_16x16x32_bf16 v[136:139], v[18:21], v[180:183], v[136:139]
	v_mfma_f32_16x16x32_bf16 v[132:135], v[26:29], v[180:183], v[132:135]
	v_mfma_f32_16x16x32_bf16 v[54:57], v[18:21], v[196:199], v[54:57]
	v_mfma_f32_16x16x32_bf16 v[50:53], v[26:29], v[196:199], v[50:53]
	v_mfma_f32_16x16x32_bf16 v[38:41], v[22:25], v[168:171], v[38:41]
	v_mfma_f32_16x16x32_bf16 v[34:37], v[30:33], v[168:171], v[34:37]
	v_mfma_f32_16x16x32_bf16 v[152:155], v[22:25], v[176:179], v[152:155]
	v_mfma_f32_16x16x32_bf16 v[148:151], v[30:33], v[176:179], v[148:151]
	v_mfma_f32_16x16x32_bf16 v[136:139], v[22:25], v[184:187], v[136:139]
	v_mfma_f32_16x16x32_bf16 v[132:135], v[30:33], v[184:187], v[132:135]
	v_mfma_f32_16x16x32_bf16 v[54:57], v[22:25], v[200:203], v[54:57]
	v_mfma_f32_16x16x32_bf16 v[50:53], v[30:33], v[200:203], v[50:53]
	s_barrier
	s_mov_b32 m0, s68
	s_mov_b32 s46, s42
	s_mov_b32 s47, s43
	ds_read_b128 v[164:167], v194 offset:16384
	ds_read_b128 v[168:171], v194 offset:17408
	ds_read_b128 v[172:175], v194 offset:18432
	ds_read_b128 v[176:179], v194 offset:19456
	ds_read_b128 v[180:183], v194 offset:20480
	ds_read_b128 v[184:187], v194 offset:21504
	ds_read_b128 v[196:199], v194 offset:22528
	ds_read_b128 v[200:203], v194 offset:23552
	buffer_load_dwordx4 v188, s[44:47], s12 offen lds
	s_mov_b32 m0, s69
	s_add_i32 s14, s12, 0x40000
	buffer_load_dwordx4 v190, s[44:47], s12 offen lds
	s_mov_b32 m0, s70
	s_nop 0
	buffer_load_dwordx4 v188, s[44:47], s14 offen lds
	s_mov_b32 m0, s72
	s_nop 0
	buffer_load_dwordx4 v190, s[44:47], s14 offen lds
	s_mov_b32 m0, s15
	s_nop 0
	buffer_load_dwordx4 v115, s[40:43], s13 offen lds
	s_mov_b32 m0, s73
	s_nop 0
	buffer_load_dwordx4 v189, s[40:43], s13 offen lds
	s_waitcnt vmcnt(8)
	s_waitcnt lgkmcnt(0)
	s_barrier
	s_waitcnt lgkmcnt(7)
	v_mfma_f32_16x16x32_bf16 v[128:131], v[2:5], v[164:167], v[128:131]
	v_mfma_f32_16x16x32_bf16 v[124:127], v[10:13], v[164:167], v[124:127]
	s_waitcnt lgkmcnt(5)
	v_mfma_f32_16x16x32_bf16 v[110:113], v[2:5], v[172:175], v[110:113]
	v_mfma_f32_16x16x32_bf16 v[106:109], v[10:13], v[172:175], v[106:109]
	s_waitcnt lgkmcnt(3)
	v_mfma_f32_16x16x32_bf16 v[94:97], v[2:5], v[180:183], v[94:97]
	v_mfma_f32_16x16x32_bf16 v[90:93], v[10:13], v[180:183], v[90:93]
	s_waitcnt lgkmcnt(1)
	v_mfma_f32_16x16x32_bf16 v[2:5], v[2:5], v[196:199], v[78:81]
	v_mfma_f32_16x16x32_bf16 v[128:131], v[6:9], v[168:171], v[128:131]
	v_mfma_f32_16x16x32_bf16 v[124:127], v[14:17], v[168:171], v[124:127]
	v_mfma_f32_16x16x32_bf16 v[110:113], v[6:9], v[176:179], v[110:113]
	v_mfma_f32_16x16x32_bf16 v[106:109], v[14:17], v[176:179], v[106:109]
	v_mfma_f32_16x16x32_bf16 v[94:97], v[6:9], v[184:187], v[94:97]
	v_mfma_f32_16x16x32_bf16 v[90:93], v[14:17], v[184:187], v[90:93]
	s_waitcnt lgkmcnt(0)
	v_mfma_f32_16x16x32_bf16 v[2:5], v[6:9], v[200:203], v[2:5]
	v_mfma_f32_16x16x32_bf16 v[6:9], v[10:13], v[196:199], v[74:77]
	v_mfma_f32_16x16x32_bf16 v[6:9], v[14:17], v[200:203], v[6:9]
	v_mfma_f32_16x16x32_bf16 v[74:77], v[18:21], v[172:175], v[102:105]
	v_mfma_f32_16x16x32_bf16 v[102:105], v[22:25], v[176:179], v[74:77]
	v_mfma_f32_16x16x32_bf16 v[74:77], v[26:29], v[172:175], v[98:101]
	v_mfma_f32_16x16x32_bf16 v[98:101], v[30:33], v[176:179], v[74:77]
	v_mfma_f32_16x16x32_bf16 v[74:77], v[18:21], v[180:183], v[86:89]
	v_mfma_f32_16x16x32_bf16 v[10:13], v[18:21], v[164:167], v[120:123]
	v_mfma_f32_16x16x32_bf16 v[86:89], v[22:25], v[184:187], v[74:77]
	v_mfma_f32_16x16x32_bf16 v[74:77], v[26:29], v[180:183], v[82:85]
	v_mfma_f32_16x16x32_bf16 v[18:21], v[18:21], v[196:199], v[70:73]
	v_mfma_f32_16x16x32_bf16 v[10:13], v[22:25], v[168:171], v[10:13]
	v_mfma_f32_16x16x32_bf16 v[14:17], v[26:29], v[164:167], v[116:119]
	v_mfma_f32_16x16x32_bf16 v[82:85], v[30:33], v[184:187], v[74:77]
	v_mfma_f32_16x16x32_bf16 v[18:21], v[22:25], v[200:203], v[18:21]
	v_mfma_f32_16x16x32_bf16 v[22:25], v[26:29], v[196:199], v[66:69]
	v_mfma_f32_16x16x32_bf16 v[14:17], v[30:33], v[168:171], v[14:17]
	v_mfma_f32_16x16x32_bf16 v[22:25], v[30:33], v[200:203], v[22:25]
	s_barrier
; #define PG8_STAGE(bufoff, goff, voff) do { _Pragma("unroll") for (int _i = 0; _i < 2; ++_i) \
;         __builtin_amdgcn_raw_ptr_buffer_load_lds(R_##voff, (LAS void*)(lds + (bufoff) + ldsw + _i * 8192), 16, (int)(voff)[_i], (int)(goff), 0, 0); } while (0)
; #define PG8_WAIT_V(n) asm volatile("s_waitcnt vmcnt(" #n ")" ::: "memory")
; #define PG8_WAIT_L(n) asm volatile("s_waitcnt lgkmcnt(" #n ")" ::: "memory")
; #define PG8_BAR __builtin_amdgcn_s_barrier()
; #define PG8_SCHED __builtin_amdgcn_sched_barrier(0)
; template <class Epi, class Sched, bool ALIGN_EPI, bool SP2>
; __device__ __forceinline__ void gemm_phase(LAS unsigned char* lds, const Gemm g, const Sched& S, const Epi& E, int tid_in) {
;     ...
;         for (int t = 0; t < nt; t += 2) {
;             const bool last = (t == nt - 2);
;             const unsigned a1 = cA + (unsigned)(t + 1) * kstep;
;             const unsigned a2 = last ? nA : cA + (unsigned)(t + 2) * kstep, b2 = last ? nB : cB + (unsigned)(t + 2) * kstep;
;             const unsigned a3 = a2 + kstep, b3 = b2 + kstep;
;             if constexpr (Epi::MIDK) { if (t == g.kmid) E.midk(acc, wr, fr); }
;             if constexpr (SP2) {
;             PG8_LDB(B0, 0, 0); PG8_LDB(B1, 0, 1); PG8_SCHED; PG8_LDA(At, 0, 0); PG8_STAGE(PG8_SA(1, 1), a1 + hstepA, voffA);
;             PG8_WAIT_V(8); PG8_WAIT_L(0); PG8_BAR; PG8_MMA(0, 0, At, B0); PG8_MMA(0, 1, At, B1); PG8_BAR; PG8_SCHED;
;             PG8_LDA(At, 0, 1); PG8_STAGE(PG8_SB(0, 0), b2, voffB); PG8_STAGE(PG8_SB(0, 1), b2 + hstepB, voffB); PG8_STAGE(PG8_SA(0, 0), a2, voffA);
;             PG8_WAIT_V(8); PG8_WAIT_L(0); PG8_BAR; PG8_MMA(1, 0, At, B0); PG8_MMA(1, 1, At, B1); PG8_BAR; PG8_SCHED;
;             PG8_LDB(B0, 1, 0); PG8_LDB(B1, 1, 1); PG8_SCHED; PG8_LDA(At, 1, 0); PG8_STAGE(PG8_SA(0, 1), a2 + hstepA, voffA);
;             PG8_WAIT_V(8); PG8_WAIT_L(0); PG8_BAR; PG8_MMA(0, 0, At, B0); PG8_MMA(0, 1, At, B1); PG8_BAR; PG8_SCHED;
;             PG8_LDA(At, 1, 1); PG8_STAGE(PG8_SB(1, 0), b3, voffB); PG8_STAGE(PG8_SB(1, 1), b3 + hstepB, voffB); PG8_STAGE(PG8_SA(1, 0), a3, voffA);
;             PG8_WAIT_V(8); PG8_WAIT_L(0); PG8_BAR; PG8_MMA(1, 0, At, B0); PG8_MMA(1, 1, At, B1); PG8_BAR; PG8_SCHED;
	v_add_u32_e32 v0, 0x18000, v193
	ds_read_b128 v[26:29], v0
	ds_read_b128 v[30:33], v0 offset:1024
	ds_read_b128 v[66:69], v0 offset:2048
	ds_read_b128 v[70:73], v0 offset:3072
	v_add_u32_e32 v0, 0x1c000, v193
	ds_read_b128 v[164:167], v0
	ds_read_b128 v[168:171], v0 offset:1024
	ds_read_b128 v[172:175], v0 offset:2048
	ds_read_b128 v[176:179], v0 offset:3072
	s_add_i32 s13, s13, 0x100000
	s_mov_b32 m0, s74
	ds_read_b128 v[74:77], v194 offset:32768
	ds_read_b128 v[78:81], v194 offset:33792
	ds_read_b128 v[116:119], v194 offset:34816
	ds_read_b128 v[120:123], v194 offset:35840
	ds_read_b128 v[180:183], v194 offset:36864
	ds_read_b128 v[184:187], v194 offset:37888
	ds_read_b128 v[196:199], v194 offset:38912
	ds_read_b128 v[200:203], v194 offset:39936
	buffer_load_dwordx4 v115, s[40:43], s13 offen lds
	s_mov_b32 m0, s75
	s_nop 0
	buffer_load_dwordx4 v189, s[40:43], s13 offen lds
	s_waitcnt vmcnt(8)
	s_waitcnt lgkmcnt(0)
	s_barrier
	s_waitcnt lgkmcnt(7)
	v_mfma_f32_16x16x32_bf16 v[46:49], v[26:29], v[74:77], v[46:49]
	v_mfma_f32_16x16x32_bf16 v[42:45], v[66:69], v[74:77], v[42:45]
	s_waitcnt lgkmcnt(5)
	v_mfma_f32_16x16x32_bf16 v[160:163], v[26:29], v[116:119], v[160:163]
	v_mfma_f32_16x16x32_bf16 v[156:159], v[66:69], v[116:119], v[156:159]
	s_waitcnt lgkmcnt(3)
	v_mfma_f32_16x16x32_bf16 v[144:147], v[26:29], v[180:183], v[144:147]
	v_mfma_f32_16x16x32_bf16 v[140:143], v[66:69], v[180:183], v[140:143]
	s_waitcnt lgkmcnt(1)
	v_mfma_f32_16x16x32_bf16 v[62:65], v[26:29], v[196:199], v[62:65]
	v_mfma_f32_16x16x32_bf16 v[58:61], v[66:69], v[196:199], v[58:61]
	v_mfma_f32_16x16x32_bf16 v[46:49], v[30:33], v[78:81], v[46:49]
	v_mfma_f32_16x16x32_bf16 v[42:45], v[70:73], v[78:81], v[42:45]
	v_mfma_f32_16x16x32_bf16 v[160:163], v[30:33], v[120:123], v[160:163]
	v_mfma_f32_16x16x32_bf16 v[156:159], v[70:73], v[120:123], v[156:159]
	v_mfma_f32_16x16x32_bf16 v[144:147], v[30:33], v[184:187], v[144:147]
	v_mfma_f32_16x16x32_bf16 v[140:143], v[70:73], v[184:187], v[140:143]
	s_waitcnt lgkmcnt(0)
	v_mfma_f32_16x16x32_bf16 v[62:65], v[30:33], v[200:203], v[62:65]
	v_mfma_f32_16x16x32_bf16 v[58:61], v[70:73], v[200:203], v[58:61]
	v_mfma_f32_16x16x32_bf16 v[38:41], v[164:167], v[74:77], v[38:41]
	v_mfma_f32_16x16x32_bf16 v[34:37], v[172:175], v[74:77], v[34:37]
	v_mfma_f32_16x16x32_bf16 v[74:77], v[164:167], v[116:119], v[152:155]
	v_mfma_f32_16x16x32_bf16 v[152:155], v[168:171], v[120:123], v[74:77]
	v_mfma_f32_16x16x32_bf16 v[74:77], v[172:175], v[116:119], v[148:151]
	v_mfma_f32_16x16x32_bf16 v[148:151], v[176:179], v[120:123], v[74:77]
	v_mfma_f32_16x16x32_bf16 v[74:77], v[164:167], v[180:183], v[136:139]
	v_mfma_f32_16x16x32_bf16 v[136:139], v[168:171], v[184:187], v[74:77]
	v_mfma_f32_16x16x32_bf16 v[74:77], v[172:175], v[180:183], v[132:135]
	v_mfma_f32_16x16x32_bf16 v[54:57], v[164:167], v[196:199], v[54:57]
	v_mfma_f32_16x16x32_bf16 v[50:53], v[172:175], v[196:199], v[50:53]
	v_mfma_f32_16x16x32_bf16 v[38:41], v[168:171], v[78:81], v[38:41]
	v_mfma_f32_16x16x32_bf16 v[34:37], v[176:179], v[78:81], v[34:37]
	v_mfma_f32_16x16x32_bf16 v[132:135], v[176:179], v[184:187], v[74:77]
	v_mfma_f32_16x16x32_bf16 v[54:57], v[168:171], v[200:203], v[54:57]
	v_mfma_f32_16x16x32_bf16 v[50:53], v[176:179], v[200:203], v[50:53]
	s_barrier
	s_mov_b32 m0, s85
	s_or_b32 s13, s12, 0x80
	ds_read_b128 v[116:119], v194 offset:49152
	ds_read_b128 v[180:183], v194 offset:50176
	ds_read_b128 v[184:187], v194 offset:51200
	ds_read_b128 v[196:199], v194 offset:52224
	ds_read_b128 v[200:203], v194 offset:53248
	ds_read_b128 v[204:207], v194 offset:54272
	ds_read_b128 v[208:211], v194 offset:55296
	ds_read_b128 v[220:223], v194 offset:56320
	buffer_load_dwordx4 v188, s[44:47], s13 offen lds
	s_mov_b32 m0, s93
	s_add_i32 s12, s12, 0x40080
	buffer_load_dwordx4 v190, s[44:47], s13 offen lds
	s_mov_b32 m0, s67
	s_add_i32 s10, s10, 2
	buffer_load_dwordx4 v188, s[44:47], s12 offen lds
	s_mov_b32 m0, s49
	s_addk_i32 s4, 0x100
	buffer_load_dwordx4 v190, s[44:47], s12 offen lds
	s_mov_b32 m0, s94
	s_addk_i32 s5, 0x100
	buffer_load_dwordx4 v115, s[40:43], s11 offen lds
	s_mov_b32 m0, s95
	s_cmp_gt_u32 s10, 61
	buffer_load_dwordx4 v189, s[40:43], s11 offen lds
	s_waitcnt vmcnt(8)
	s_waitcnt lgkmcnt(0)
	s_barrier
	s_waitcnt lgkmcnt(7)
	v_mfma_f32_16x16x32_bf16 v[74:77], v[26:29], v[116:119], v[128:131]
	s_waitcnt lgkmcnt(6)
	v_mfma_f32_16x16x32_bf16 v[128:131], v[30:33], v[180:183], v[74:77]
	v_mfma_f32_16x16x32_bf16 v[74:77], v[66:69], v[116:119], v[124:127]
	v_mfma_f32_16x16x32_bf16 v[124:127], v[70:73], v[180:183], v[74:77]
	s_waitcnt lgkmcnt(5)
	v_mfma_f32_16x16x32_bf16 v[74:77], v[26:29], v[184:187], v[110:113]
	s_waitcnt lgkmcnt(4)
	v_mfma_f32_16x16x32_bf16 v[110:113], v[30:33], v[196:199], v[74:77]
	v_mfma_f32_16x16x32_bf16 v[74:77], v[66:69], v[184:187], v[106:109]
	v_mfma_f32_16x16x32_bf16 v[106:109], v[70:73], v[196:199], v[74:77]
	s_waitcnt lgkmcnt(3)
	v_mfma_f32_16x16x32_bf16 v[74:77], v[26:29], v[200:203], v[94:97]
	s_waitcnt lgkmcnt(1)
	v_mfma_f32_16x16x32_bf16 v[2:5], v[26:29], v[208:211], v[2:5]
	v_mfma_f32_16x16x32_bf16 v[94:97], v[30:33], v[204:207], v[74:77]
	v_mfma_f32_16x16x32_bf16 v[74:77], v[66:69], v[200:203], v[90:93]
	s_waitcnt lgkmcnt(0)
	v_mfma_f32_16x16x32_bf16 v[78:81], v[30:33], v[220:223], v[2:5]
	v_mfma_f32_16x16x32_bf16 v[2:5], v[66:69], v[208:211], v[6:9]
	v_mfma_f32_16x16x32_bf16 v[90:93], v[70:73], v[204:207], v[74:77]
	v_mfma_f32_16x16x32_bf16 v[74:77], v[70:73], v[220:223], v[2:5]
	v_mfma_f32_16x16x32_bf16 v[2:5], v[164:167], v[116:119], v[10:13]
	v_mfma_f32_16x16x32_bf16 v[120:123], v[168:171], v[180:183], v[2:5]
	v_mfma_f32_16x16x32_bf16 v[2:5], v[172:175], v[116:119], v[14:17]
	v_mfma_f32_16x16x32_bf16 v[116:119], v[176:179], v[180:183], v[2:5]
	v_mfma_f32_16x16x32_bf16 v[2:5], v[164:167], v[184:187], v[102:105]
	v_mfma_f32_16x16x32_bf16 v[102:105], v[168:171], v[196:199], v[2:5]
	v_mfma_f32_16x16x32_bf16 v[2:5], v[172:175], v[184:187], v[98:101]
	v_mfma_f32_16x16x32_bf16 v[98:101], v[176:179], v[196:199], v[2:5]
	v_mfma_f32_16x16x32_bf16 v[2:5], v[164:167], v[200:203], v[86:89]
	v_mfma_f32_16x16x32_bf16 v[86:89], v[168:171], v[204:207], v[2:5]
	v_mfma_f32_16x16x32_bf16 v[2:5], v[172:175], v[200:203], v[82:85]
	v_mfma_f32_16x16x32_bf16 v[82:85], v[176:179], v[204:207], v[2:5]
	v_mfma_f32_16x16x32_bf16 v[2:5], v[164:167], v[208:211], v[18:21]
	v_mfma_f32_16x16x32_bf16 v[70:73], v[168:171], v[220:223], v[2:5]
	v_mfma_f32_16x16x32_bf16 v[2:5], v[172:175], v[208:211], v[22:25]
	v_mfma_f32_16x16x32_bf16 v[66:69], v[176:179], v[220:223], v[2:5]
	s_barrier
	s_cbranch_scc0 .LBB0_137
	v_readlane_b32 s2, v255, 30
	v_readlane_b32 s3, v255, 31
	s_and_b64 vcc, exec, s[2:3]
	s_cbranch_vccz .LBB0_140
	s_barrier

; #define PG8_STAGE(bufoff, goff, voff) do { _Pragma("unroll") for (int _i = 0; _i < 2; ++_i) \
;         __builtin_amdgcn_raw_ptr_buffer_load_lds(R_##voff, (LAS void*)(lds + (bufoff) + ldsw + _i * 8192), 16, (int)(voff)[_i], (int)(goff), 0, 0); } while (0)
; #define PG8_WAIT_V(n) asm volatile("s_waitcnt vmcnt(" #n ")" ::: "memory")
; #define PG8_WAIT_L(n) asm volatile("s_waitcnt lgkmcnt(" #n ")" ::: "memory")
; #define PG8_BAR __builtin_amdgcn_s_barrier()
; #define PG8_SCHED __builtin_amdgcn_sched_barrier(0)
; template <class Epi, class Sched, bool ALIGN_EPI, bool SP2>
; __device__ __forceinline__ void gemm_phase(LAS unsigned char* lds, const Gemm g, const Sched& S, const Epi& E, int tid_in) {
;     ...
;             PG8_LDB(B0, 0, 0); PG8_LDB(B1, 0, 1); PG8_SCHED; PG8_LDA(At, 0, 0); PG8_STAGE(PG8_SA(1, 1), a1 + hstepA, voffA);
;             PG8_WAIT_V(8); PG8_WAIT_L(0); PG8_BAR; PG8_MMA(0, 0, At, B0); PG8_MMA(0, 1, At, B1); PG8_BAR; PG8_SCHED;
;             PG8_LDA(At, 0, 1); PG8_STAGE(PG8_SB(0, 0), b2, voffB); PG8_STAGE(PG8_SB(0, 1), b2 + hstepB, voffB); PG8_STAGE(PG8_SA(0, 0), a2, voffA);
;             PG8_WAIT_V(8); PG8_WAIT_L(0); PG8_BAR; PG8_MMA(1, 0, At, B0); PG8_MMA(1, 1, At, B1); PG8_BAR; PG8_SCHED;
.LBB0_338:
	v_add_u32_e32 v144, 0x10000, v154
	v_add_u32_e32 v148, 0x14000, v154
	ds_read_b128 v[132:135], v144
	ds_read_b128 v[136:139], v144 offset:1024
	ds_read_b128 v[140:143], v144 offset:2048
	ds_read_b128 v[144:147], v144 offset:3072
	ds_read_b128 v[156:159], v148
	ds_read_b128 v[160:163], v148 offset:1024
	ds_read_b128 v[164:167], v148 offset:2048
	ds_read_b128 v[168:171], v148 offset:3072
	s_add_i32 s14, s57, 0xfff00080
	s_cmp_eq_u32 s59, 60
	s_cselect_b32 s14, s4, s14
	s_cselect_b32 s61, s5, s58
	s_or_b32 s60, s14, 0x80
	s_mov_b32 m0, s34
	ds_read_b128 v[172:175], v155
	ds_read_b128 v[176:179], v155 offset:1024
	ds_read_b128 v[180:183], v155 offset:2048
	ds_read_b128 v[184:187], v155 offset:3072
	ds_read_b128 v[188:191], v155 offset:4096
	ds_read_b128 v[192:195], v155 offset:5120
	ds_read_b128 v[196:199], v155 offset:6144
	ds_read_b128 v[200:203], v155 offset:7168
	buffer_load_dwordx4 v0, s[84:87], s57 offen lds
	s_mov_b32 m0, s47
	s_nop 0
	buffer_load_dwordx4 v150, s[84:87], s57 offen lds
	s_waitcnt vmcnt(8)
	s_waitcnt lgkmcnt(0)
	s_barrier
	s_setprio 1
	s_waitcnt lgkmcnt(7)
	v_mfma_f32_16x16x32_bf16 v[128:131], v[132:135], v[172:175], v[128:131]
	v_mfma_f32_16x16x32_bf16 v[124:127], v[140:143], v[172:175], v[124:127]
	s_waitcnt lgkmcnt(5)
	v_mfma_f32_16x16x32_bf16 v[116:119], v[132:135], v[180:183], v[116:119]
	v_mfma_f32_16x16x32_bf16 v[106:109], v[140:143], v[180:183], v[106:109]
	s_waitcnt lgkmcnt(3)
	v_mfma_f32_16x16x32_bf16 v[98:101], v[132:135], v[188:191], v[98:101]
	v_mfma_f32_16x16x32_bf16 v[90:93], v[140:143], v[188:191], v[90:93]
	s_waitcnt lgkmcnt(1)
	v_mfma_f32_16x16x32_bf16 v[82:85], v[132:135], v[196:199], v[82:85]
	v_mfma_f32_16x16x32_bf16 v[74:77], v[140:143], v[196:199], v[74:77]
	v_mfma_f32_16x16x32_bf16 v[128:131], v[136:139], v[176:179], v[128:131]
	v_mfma_f32_16x16x32_bf16 v[124:127], v[144:147], v[176:179], v[124:127]
	v_mfma_f32_16x16x32_bf16 v[116:119], v[136:139], v[184:187], v[116:119]
	v_mfma_f32_16x16x32_bf16 v[106:109], v[144:147], v[184:187], v[106:109]
	v_mfma_f32_16x16x32_bf16 v[98:101], v[136:139], v[192:195], v[98:101]
	v_mfma_f32_16x16x32_bf16 v[90:93], v[144:147], v[192:195], v[90:93]
	s_waitcnt lgkmcnt(0)
	v_mfma_f32_16x16x32_bf16 v[82:85], v[136:139], v[200:203], v[82:85]
	v_mfma_f32_16x16x32_bf16 v[74:77], v[144:147], v[200:203], v[74:77]
	v_mfma_f32_16x16x32_bf16 v[120:123], v[156:159], v[172:175], v[120:123]
	v_mfma_f32_16x16x32_bf16 v[110:113], v[164:167], v[172:175], v[110:113]
	v_mfma_f32_16x16x32_bf16 v[102:105], v[156:159], v[180:183], v[102:105]
	v_mfma_f32_16x16x32_bf16 v[94:97], v[164:167], v[180:183], v[94:97]
	v_mfma_f32_16x16x32_bf16 v[86:89], v[156:159], v[188:191], v[86:89]
	v_mfma_f32_16x16x32_bf16 v[78:81], v[164:167], v[188:191], v[78:81]
	v_mfma_f32_16x16x32_bf16 v[70:73], v[156:159], v[196:199], v[70:73]
	v_mfma_f32_16x16x32_bf16 v[66:69], v[164:167], v[196:199], v[66:69]
	v_mfma_f32_16x16x32_bf16 v[120:123], v[160:163], v[176:179], v[120:123]
	v_mfma_f32_16x16x32_bf16 v[110:113], v[168:171], v[176:179], v[110:113]
	v_mfma_f32_16x16x32_bf16 v[102:105], v[160:163], v[184:187], v[102:105]
	v_mfma_f32_16x16x32_bf16 v[94:97], v[168:171], v[184:187], v[94:97]
	v_mfma_f32_16x16x32_bf16 v[86:89], v[160:163], v[192:195], v[86:89]
	v_mfma_f32_16x16x32_bf16 v[78:81], v[168:171], v[192:195], v[78:81]
	v_mfma_f32_16x16x32_bf16 v[70:73], v[160:163], v[200:203], v[70:73]
	v_mfma_f32_16x16x32_bf16 v[66:69], v[168:171], v[200:203], v[66:69]
	s_setprio 0
	s_barrier
	s_mov_b32 m0, s8
	ds_read_b128 v[172:175], v155 offset:16384
	ds_read_b128 v[176:179], v155 offset:17408
	ds_read_b128 v[180:183], v155 offset:18432
	ds_read_b128 v[184:187], v155 offset:19456
	ds_read_b128 v[188:191], v155 offset:20480
	ds_read_b128 v[192:195], v155 offset:21504
	ds_read_b128 v[196:199], v155 offset:22528
	ds_read_b128 v[200:203], v155 offset:23552
	buffer_load_dwordx4 v115, s[40:43], s61 offen lds
	s_mov_b32 m0, s9
	s_add_i32 s15, s61, 0x40000
	buffer_load_dwordx4 v151, s[40:43], s61 offen lds
	s_mov_b32 m0, s10
	s_nop 0
	buffer_load_dwordx4 v115, s[40:43], s15 offen lds
	s_mov_b32 m0, s11
	s_nop 0
	buffer_load_dwordx4 v151, s[40:43], s15 offen lds
	s_mov_b32 m0, s7
	s_nop 0
	buffer_load_dwordx4 v0, s[84:87], s14 offen lds
	s_mov_b32 m0, s12
	s_nop 0
	buffer_load_dwordx4 v150, s[84:87], s14 offen lds
	s_waitcnt vmcnt(8)
	s_waitcnt lgkmcnt(0)
	s_barrier
	s_setprio 1
	s_waitcnt lgkmcnt(7)
	v_mfma_f32_16x16x32_bf16 v[62:65], v[132:135], v[172:175], v[62:65]
	v_mfma_f32_16x16x32_bf16 v[58:61], v[140:143], v[172:175], v[58:61]
	s_waitcnt lgkmcnt(5)
	v_mfma_f32_16x16x32_bf16 v[50:53], v[132:135], v[180:183], v[50:53]
	v_mfma_f32_16x16x32_bf16 v[42:45], v[140:143], v[180:183], v[42:45]
	s_waitcnt lgkmcnt(3)
	v_mfma_f32_16x16x32_bf16 v[34:37], v[132:135], v[188:191], v[34:37]
	v_mfma_f32_16x16x32_bf16 v[26:29], v[140:143], v[188:191], v[26:29]
	s_waitcnt lgkmcnt(1)
	v_mfma_f32_16x16x32_bf16 v[18:21], v[132:135], v[196:199], v[18:21]
	v_mfma_f32_16x16x32_bf16 v[10:13], v[140:143], v[196:199], v[10:13]
	v_mfma_f32_16x16x32_bf16 v[62:65], v[136:139], v[176:179], v[62:65]
	v_mfma_f32_16x16x32_bf16 v[58:61], v[144:147], v[176:179], v[58:61]
	v_mfma_f32_16x16x32_bf16 v[50:53], v[136:139], v[184:187], v[50:53]
	v_mfma_f32_16x16x32_bf16 v[42:45], v[144:147], v[184:187], v[42:45]
	v_mfma_f32_16x16x32_bf16 v[34:37], v[136:139], v[192:195], v[34:37]
	v_mfma_f32_16x16x32_bf16 v[26:29], v[144:147], v[192:195], v[26:29]
	s_waitcnt lgkmcnt(0)
	v_mfma_f32_16x16x32_bf16 v[18:21], v[136:139], v[200:203], v[18:21]
	v_mfma_f32_16x16x32_bf16 v[10:13], v[144:147], v[200:203], v[10:13]
	v_mfma_f32_16x16x32_bf16 v[54:57], v[156:159], v[172:175], v[54:57]
	v_mfma_f32_16x16x32_bf16 v[46:49], v[164:167], v[172:175], v[46:49]
	v_mfma_f32_16x16x32_bf16 v[38:41], v[156:159], v[180:183], v[38:41]
	v_mfma_f32_16x16x32_bf16 v[30:33], v[164:167], v[180:183], v[30:33]
	v_mfma_f32_16x16x32_bf16 v[22:25], v[156:159], v[188:191], v[22:25]
	v_mfma_f32_16x16x32_bf16 v[14:17], v[164:167], v[188:191], v[14:17]
	v_mfma_f32_16x16x32_bf16 v[6:9], v[156:159], v[196:199], v[6:9]
	v_mfma_f32_16x16x32_bf16 v[2:5], v[164:167], v[196:199], v[2:5]
	v_mfma_f32_16x16x32_bf16 v[54:57], v[160:163], v[176:179], v[54:57]
	v_mfma_f32_16x16x32_bf16 v[46:49], v[168:171], v[176:179], v[46:49]
	v_mfma_f32_16x16x32_bf16 v[38:41], v[160:163], v[184:187], v[38:41]
	v_mfma_f32_16x16x32_bf16 v[30:33], v[168:171], v[184:187], v[30:33]
	v_mfma_f32_16x16x32_bf16 v[22:25], v[160:163], v[192:195], v[22:25]
	v_mfma_f32_16x16x32_bf16 v[14:17], v[168:171], v[192:195], v[14:17]
	v_mfma_f32_16x16x32_bf16 v[6:9], v[160:163], v[200:203], v[6:9]
	v_mfma_f32_16x16x32_bf16 v[2:5], v[168:171], v[200:203], v[2:5]
	s_setprio 0
	s_barrier
; #define PG8_STAGE(bufoff, goff, voff) do { _Pragma("unroll") for (int _i = 0; _i < 2; ++_i) \
;         __builtin_amdgcn_raw_ptr_buffer_load_lds(R_##voff, (LAS void*)(lds + (bufoff) + ldsw + _i * 8192), 16, (int)(voff)[_i], (int)(goff), 0, 0); } while (0)
; #define PG8_WAIT_V(n) asm volatile("s_waitcnt vmcnt(" #n ")" ::: "memory")
; #define PG8_WAIT_L(n) asm volatile("s_waitcnt lgkmcnt(" #n ")" ::: "memory")
; #define PG8_BAR __builtin_amdgcn_s_barrier()
; #define PG8_SCHED __builtin_amdgcn_sched_barrier(0)
; template <class Epi, class Sched, bool ALIGN_EPI, bool SP2>
; __device__ __forceinline__ void gemm_phase(LAS unsigned char* lds, const Gemm g, const Sched& S, const Epi& E, int tid_in) {
;     ...
;         for (int t = 0; t < nt; t += 2) {
;             const bool last = (t == nt - 2);
;             const unsigned a1 = cA + (unsigned)(t + 1) * kstep;
;             const unsigned a2 = last ? nA : cA + (unsigned)(t + 2) * kstep, b2 = last ? nB : cB + (unsigned)(t + 2) * kstep;
;             const unsigned a3 = a2 + kstep, b3 = b2 + kstep;
;             if constexpr (Epi::MIDK) { if (t == g.kmid) E.midk(acc, wr, fr); }
;             if constexpr (SP2) {
;             PG8_LDB(B0, 0, 0); PG8_LDB(B1, 0, 1); PG8_SCHED; PG8_LDA(At, 0, 0); PG8_STAGE(PG8_SA(1, 1), a1 + hstepA, voffA);
;             PG8_WAIT_V(8); PG8_WAIT_L(0); PG8_BAR; PG8_MMA(0, 0, At, B0); PG8_MMA(0, 1, At, B1); PG8_BAR; PG8_SCHED;
;             PG8_LDA(At, 0, 1); PG8_STAGE(PG8_SB(0, 0), b2, voffB); PG8_STAGE(PG8_SB(0, 1), b2 + hstepB, voffB); PG8_STAGE(PG8_SA(0, 0), a2, voffA);
;             PG8_WAIT_V(8); PG8_WAIT_L(0); PG8_BAR; PG8_MMA(1, 0, At, B0); PG8_MMA(1, 1, At, B1); PG8_BAR; PG8_SCHED;
;             PG8_LDB(B0, 1, 0); PG8_LDB(B1, 1, 1); PG8_SCHED; PG8_LDA(At, 1, 0); PG8_STAGE(PG8_SA(0, 1), a2 + hstepA, voffA);
;             PG8_WAIT_V(8); PG8_WAIT_L(0); PG8_BAR; PG8_MMA(0, 0, At, B0); PG8_MMA(0, 1, At, B1); PG8_BAR; PG8_SCHED;
;             PG8_LDA(At, 1, 1); PG8_STAGE(PG8_SB(1, 0), b3, voffB); PG8_STAGE(PG8_SB(1, 1), b3 + hstepB, voffB); PG8_STAGE(PG8_SA(1, 0), a3, voffA);
;             PG8_WAIT_V(8); PG8_WAIT_L(0); PG8_BAR; PG8_MMA(1, 0, At, B0); PG8_MMA(1, 1, At, B1); PG8_BAR; PG8_SCHED;
	v_add_u32_e32 v144, 0x18000, v154
	v_add_u32_e32 v148, 0x1c000, v154
	ds_read_b128 v[132:135], v144
	ds_read_b128 v[136:139], v144 offset:1024
	ds_read_b128 v[140:143], v144 offset:2048
	ds_read_b128 v[144:147], v144 offset:3072
	ds_read_b128 v[156:159], v148
	ds_read_b128 v[160:163], v148 offset:1024
	ds_read_b128 v[164:167], v148 offset:2048
	ds_read_b128 v[168:171], v148 offset:3072
	s_add_i32 s14, s14, 0x100000
	s_mov_b32 m0, s13
	ds_read_b128 v[172:175], v155 offset:32768
	ds_read_b128 v[176:179], v155 offset:33792
	ds_read_b128 v[180:183], v155 offset:34816
	ds_read_b128 v[184:187], v155 offset:35840
	ds_read_b128 v[188:191], v155 offset:36864
	ds_read_b128 v[192:195], v155 offset:37888
	ds_read_b128 v[196:199], v155 offset:38912
	ds_read_b128 v[200:203], v155 offset:39936
	buffer_load_dwordx4 v0, s[84:87], s14 offen lds
	s_mov_b32 m0, s16
	s_nop 0
	buffer_load_dwordx4 v150, s[84:87], s14 offen lds
	s_waitcnt vmcnt(8)
	s_waitcnt lgkmcnt(0)
	s_barrier
	s_setprio 1
	s_waitcnt lgkmcnt(7)
	v_mfma_f32_16x16x32_bf16 v[128:131], v[132:135], v[172:175], v[128:131]
	v_mfma_f32_16x16x32_bf16 v[124:127], v[140:143], v[172:175], v[124:127]
	s_waitcnt lgkmcnt(5)
	v_mfma_f32_16x16x32_bf16 v[116:119], v[132:135], v[180:183], v[116:119]
	v_mfma_f32_16x16x32_bf16 v[106:109], v[140:143], v[180:183], v[106:109]
	s_waitcnt lgkmcnt(3)
	v_mfma_f32_16x16x32_bf16 v[98:101], v[132:135], v[188:191], v[98:101]
	v_mfma_f32_16x16x32_bf16 v[90:93], v[140:143], v[188:191], v[90:93]
	s_waitcnt lgkmcnt(1)
	v_mfma_f32_16x16x32_bf16 v[82:85], v[132:135], v[196:199], v[82:85]
	v_mfma_f32_16x16x32_bf16 v[74:77], v[140:143], v[196:199], v[74:77]
	v_mfma_f32_16x16x32_bf16 v[128:131], v[136:139], v[176:179], v[128:131]
	v_mfma_f32_16x16x32_bf16 v[124:127], v[144:147], v[176:179], v[124:127]
	v_mfma_f32_16x16x32_bf16 v[116:119], v[136:139], v[184:187], v[116:119]
	v_mfma_f32_16x16x32_bf16 v[106:109], v[144:147], v[184:187], v[106:109]
	v_mfma_f32_16x16x32_bf16 v[98:101], v[136:139], v[192:195], v[98:101]
	v_mfma_f32_16x16x32_bf16 v[90:93], v[144:147], v[192:195], v[90:93]
	s_waitcnt lgkmcnt(0)
	v_mfma_f32_16x16x32_bf16 v[82:85], v[136:139], v[200:203], v[82:85]
	v_mfma_f32_16x16x32_bf16 v[74:77], v[144:147], v[200:203], v[74:77]
	v_mfma_f32_16x16x32_bf16 v[120:123], v[156:159], v[172:175], v[120:123]
	v_mfma_f32_16x16x32_bf16 v[110:113], v[164:167], v[172:175], v[110:113]
	v_mfma_f32_16x16x32_bf16 v[102:105], v[156:159], v[180:183], v[102:105]
	v_mfma_f32_16x16x32_bf16 v[94:97], v[164:167], v[180:183], v[94:97]
	v_mfma_f32_16x16x32_bf16 v[86:89], v[156:159], v[188:191], v[86:89]
	v_mfma_f32_16x16x32_bf16 v[78:81], v[164:167], v[188:191], v[78:81]
	v_mfma_f32_16x16x32_bf16 v[70:73], v[156:159], v[196:199], v[70:73]
	v_mfma_f32_16x16x32_bf16 v[66:69], v[164:167], v[196:199], v[66:69]
	v_mfma_f32_16x16x32_bf16 v[120:123], v[160:163], v[176:179], v[120:123]
	v_mfma_f32_16x16x32_bf16 v[110:113], v[168:171], v[176:179], v[110:113]
	v_mfma_f32_16x16x32_bf16 v[102:105], v[160:163], v[184:187], v[102:105]
	v_mfma_f32_16x16x32_bf16 v[94:97], v[168:171], v[184:187], v[94:97]
	v_mfma_f32_16x16x32_bf16 v[86:89], v[160:163], v[192:195], v[86:89]
	v_mfma_f32_16x16x32_bf16 v[78:81], v[168:171], v[192:195], v[78:81]
	v_mfma_f32_16x16x32_bf16 v[70:73], v[160:163], v[200:203], v[70:73]
	v_mfma_f32_16x16x32_bf16 v[66:69], v[168:171], v[200:203], v[66:69]
	s_setprio 0
	s_barrier
	s_mov_b32 m0, s17
	s_or_b32 s14, s61, 0x80
	ds_read_b128 v[172:175], v155 offset:49152
	ds_read_b128 v[176:179], v155 offset:50176
	ds_read_b128 v[180:183], v155 offset:51200
	ds_read_b128 v[184:187], v155 offset:52224
	ds_read_b128 v[188:191], v155 offset:53248
	ds_read_b128 v[192:195], v155 offset:54272
	ds_read_b128 v[196:199], v155 offset:55296
	ds_read_b128 v[200:203], v155 offset:56320
	buffer_load_dwordx4 v115, s[40:43], s14 offen lds
	s_mov_b32 m0, s19
	s_add_i32 s61, s61, 0x40080
	buffer_load_dwordx4 v151, s[40:43], s14 offen lds
	s_mov_b32 m0, s29
	s_add_i32 s59, s59, 2
	buffer_load_dwordx4 v115, s[40:43], s61 offen lds
	s_mov_b32 m0, s30
	s_addk_i32 s57, 0x100
	buffer_load_dwordx4 v151, s[40:43], s61 offen lds
	s_mov_b32 m0, s25
	s_addk_i32 s58, 0x100
	buffer_load_dwordx4 v0, s[84:87], s60 offen lds
	s_mov_b32 m0, s27
	s_cmp_gt_u32 s59, 61
	buffer_load_dwordx4 v150, s[84:87], s60 offen lds
	s_waitcnt vmcnt(8)
	s_waitcnt lgkmcnt(0)
	s_barrier
	s_setprio 1
	s_waitcnt lgkmcnt(7)
	v_mfma_f32_16x16x32_bf16 v[62:65], v[132:135], v[172:175], v[62:65]
	v_mfma_f32_16x16x32_bf16 v[58:61], v[140:143], v[172:175], v[58:61]
	s_waitcnt lgkmcnt(5)
	v_mfma_f32_16x16x32_bf16 v[50:53], v[132:135], v[180:183], v[50:53]
	v_mfma_f32_16x16x32_bf16 v[42:45], v[140:143], v[180:183], v[42:45]
	s_waitcnt lgkmcnt(3)
	v_mfma_f32_16x16x32_bf16 v[34:37], v[132:135], v[188:191], v[34:37]
	v_mfma_f32_16x16x32_bf16 v[26:29], v[140:143], v[188:191], v[26:29]
	s_waitcnt lgkmcnt(1)
	v_mfma_f32_16x16x32_bf16 v[18:21], v[132:135], v[196:199], v[18:21]
	v_mfma_f32_16x16x32_bf16 v[10:13], v[140:143], v[196:199], v[10:13]
	v_mfma_f32_16x16x32_bf16 v[62:65], v[136:139], v[176:179], v[62:65]
	v_mfma_f32_16x16x32_bf16 v[58:61], v[144:147], v[176:179], v[58:61]
	v_mfma_f32_16x16x32_bf16 v[50:53], v[136:139], v[184:187], v[50:53]
	v_mfma_f32_16x16x32_bf16 v[42:45], v[144:147], v[184:187], v[42:45]
	v_mfma_f32_16x16x32_bf16 v[34:37], v[136:139], v[192:195], v[34:37]
	v_mfma_f32_16x16x32_bf16 v[26:29], v[144:147], v[192:195], v[26:29]
	s_waitcnt lgkmcnt(0)
	v_mfma_f32_16x16x32_bf16 v[18:21], v[136:139], v[200:203], v[18:21]
	v_mfma_f32_16x16x32_bf16 v[10:13], v[144:147], v[200:203], v[10:13]
	v_mfma_f32_16x16x32_bf16 v[54:57], v[156:159], v[172:175], v[54:57]
	v_mfma_f32_16x16x32_bf16 v[46:49], v[164:167], v[172:175], v[46:49]
	v_mfma_f32_16x16x32_bf16 v[38:41], v[156:159], v[180:183], v[38:41]
	v_mfma_f32_16x16x32_bf16 v[30:33], v[164:167], v[180:183], v[30:33]
	v_mfma_f32_16x16x32_bf16 v[22:25], v[156:159], v[188:191], v[22:25]
	v_mfma_f32_16x16x32_bf16 v[14:17], v[164:167], v[188:191], v[14:17]
	v_mfma_f32_16x16x32_bf16 v[6:9], v[156:159], v[196:199], v[6:9]
	v_mfma_f32_16x16x32_bf16 v[2:5], v[164:167], v[196:199], v[2:5]
	v_mfma_f32_16x16x32_bf16 v[54:57], v[160:163], v[176:179], v[54:57]
	v_mfma_f32_16x16x32_bf16 v[46:49], v[168:171], v[176:179], v[46:49]
	v_mfma_f32_16x16x32_bf16 v[38:41], v[160:163], v[184:187], v[38:41]
	v_mfma_f32_16x16x32_bf16 v[30:33], v[168:171], v[184:187], v[30:33]
	v_mfma_f32_16x16x32_bf16 v[22:25], v[160:163], v[192:195], v[22:25]
	v_mfma_f32_16x16x32_bf16 v[14:17], v[168:171], v[192:195], v[14:17]
	v_mfma_f32_16x16x32_bf16 v[6:9], v[160:163], v[200:203], v[6:9]
	v_mfma_f32_16x16x32_bf16 v[2:5], v[168:171], v[200:203], v[2:5]
	s_setprio 0
	s_barrier
	s_cbranch_scc0 .LBB0_338
	s_and_b64 vcc, exec, s[44:45]
	s_cbranch_vccz .LBB0_341
	s_barrier
